# final RMSNorm phase: batch the row loads (was 9 serialized round trips per row), gain vector loaded once per wave
# baseline (speedup 1.0000x reference)
; #define SSP(k) (WSP(float, WS_SS) + (size_t)(k) * T * 32)
; __device__ __forceinline__ void final_row(const bf16_t* hrow, const float* gain, const float* ssrow, float* orow, int lane) {
;     const float ss = wave_sum(lane < 32 ? ssrow[lane] : 0.f);
;     const float r = 1.0f / sqrtf(ss * (1.f / D) + EPS);
; #pragma unroll
;     for (int j = 0; j < 8; ++j) { const u32x2 hw = *(const u32x2*)(hrow + 4 * lane + 256 * j); const f32x4 g = *(const f32x4*)(gain + 4 * lane + 256 * j);
; __global__ void __launch_bounds__(512) mega_fwd(Params p_unused) {
;     ...
;     { IDS; KParams P = kparams(); const bf16_t* H = WSP(bf16_t, WS_XN); const float* fn = P->final_norm; float* out = P->out; const float* ss = SSP(8);
;       for (int row = gw; row < T; row += NGW) final_row(H + (size_t)row * D, fn, ss + (size_t)row * 32, out + (size_t)row * D, lane); }
.LBB0_3115:
	s_or_b64 exec, exec, s[0:1]
	s_waitcnt lgkmcnt(0)
	s_barrier
	v_readlane_b32 s1, v246, 2
	v_readfirstlane_b32 s0, v204
	s_ashr_i32 s0, s0, 6
	s_add_i32 s8, s0, s1
	s_cmpk_gt_i32 s8, 0x1fff
	s_cbranch_scc1 .LBB0_3120
	v_and_b32_e32 v0, 64, v202
	v_add_u32_e32 v0, 64, v0
	v_xor_b32_e32 v1, 1, v202
	v_cmp_lt_i32_e32 vcc, v1, v0
	s_load_dwordx4 s[4:7], s[76:77], 0xc8
	s_load_dwordx2 s[10:11], s[76:77], 0xd8
	v_cndmask_b32_e32 v1, v202, v1, vcc
	v_lshlrev_b32_e32 v16, 2, v1
	v_xor_b32_e32 v1, 2, v202
	v_cmp_lt_i32_e32 vcc, v1, v0
	v_and_b32_e32 v14, 63, v204
	v_mov_b32_e32 v11, 0
	v_cndmask_b32_e32 v1, v202, v1, vcc
	v_lshlrev_b32_e32 v17, 2, v1
	v_xor_b32_e32 v1, 4, v202
	v_cmp_lt_i32_e32 vcc, v1, v0
	v_lshlrev_b32_e32 v12, 4, v14
	v_mov_b32_e32 v13, v11
	v_cndmask_b32_e32 v1, v202, v1, vcc
	v_lshlrev_b32_e32 v18, 2, v1
	v_xor_b32_e32 v1, 8, v202
	v_cmp_lt_i32_e32 vcc, v1, v0
	s_ashr_i32 s9, s8, 31
	v_lshlrev_b32_e32 v10, 2, v14
	v_cndmask_b32_e32 v1, v202, v1, vcc
	v_lshlrev_b32_e32 v19, 2, v1
	v_xor_b32_e32 v1, 16, v202
	v_cmp_lt_i32_e32 vcc, v1, v0
	s_ashr_i32 s73, s72, 31
	s_mov_b64 s[2:3], 0x1000
	v_cndmask_b32_e32 v1, v202, v1, vcc
	v_lshlrev_b32_e32 v20, 2, v1
	v_xor_b32_e32 v1, 32, v202
	v_cmp_lt_i32_e32 vcc, v1, v0
	s_lshl_b64 s[12:13], s[8:9], 13
	v_cmp_gt_u32_e64 s[0:1], 32, v14
	v_cndmask_b32_e32 v0, v202, v1, vcc
	v_lshlrev_b32_e32 v21, 2, v0
	s_waitcnt lgkmcnt(0)
	v_lshl_add_u64 v[0:1], s[4:5], 0, v[12:13]
	s_lshl_b64 s[4:5], s[8:9], 7
	v_lshl_add_u64 v[10:11], s[4:5], 0, v[10:11]
	s_mov_b64 s[4:5], 0x43c00000
	v_lshl_add_u64 v[10:11], v[10:11], 0, s[4:5]
	s_lshl_b64 s[4:5], s[72:73], 7
	v_lshl_add_u64 v[2:3], v[0:1], 0, s[2:3]
	s_mov_b64 s[2:3], 0x1400
	s_add_u32 s6, s6, s12
	v_lshl_add_u64 v[4:5], v[0:1], 0, s[2:3]
	s_mov_b64 s[2:3], 0x1800
	s_addc_u32 s7, s7, s13
	v_lshl_add_u64 v[6:7], v[0:1], 0, s[2:3]
	s_mov_b64 s[2:3], 0x1c00
	v_lshl_add_u64 v[12:13], s[6:7], 0, v[12:13]
	v_lshl_add_u64 v[8:9], v[0:1], 0, s[2:3]
	v_lshl_add_u64 v[12:13], v[12:13], 0, s[2:3]
	s_lshl_b64 s[2:3], s[8:9], 12
	s_lshl_b64 s[6:7], s[72:73], 13
	v_lshl_or_b32 v14, v14, 3, s2
	v_mov_b32_e32 v15, s3
	s_lshl_b64 s[12:13], s[72:73], 12
	v_mov_b32_e32 v22, 0x358637bd
	s_mov_b32 s9, 0xf800000
	v_mov_b32_e32 v23, 0x260
	s_mov_b32 s14, 0x1af00000
	s_movk_i32 s15, 0xf000
	s_mov_b32 s16, 0xfffff000
	s_mov_b32 s17, -1
	global_load_dwordx4 v[40:43], v[0:1], off
	global_load_dwordx4 v[44:47], v[0:1], off offset:1024
	global_load_dwordx4 v[48:51], v[0:1], off offset:2048
	global_load_dwordx4 v[52:55], v[0:1], off offset:3072
	global_load_dwordx4 v[56:59], v[2:3], off
	global_load_dwordx4 v[60:63], v[4:5], off
	global_load_dwordx4 v[64:67], v[6:7], off
	global_load_dwordx4 v[68:71], v[8:9], off
; __device__ __forceinline__ void final_row(const bf16_t* hrow, const float* gain, const float* ssrow, float* orow, int lane) {
;     const float ss = wave_sum(lane < 32 ? ssrow[lane] : 0.f);
;     const float r = 1.0f / sqrtf(ss * (1.f / D) + EPS);
; #pragma unroll
;     for (int j = 0; j < 8; ++j) { const u32x2 hw = *(const u32x2*)(hrow + 4 * lane + 256 * j); const f32x4 g = *(const f32x4*)(gain + 4 * lane + 256 * j);
;         f32x4 o; o.x = __uint_as_float(hw.x << 16) * r * g.x; o.y = __uint_as_float(hw.x & 0xffff0000u) * r * g.y; o.z = __uint_as_float(hw.y << 16) * r * g.z; o.w = __uint_as_float(hw.y & 0xffff0000u) * r * g.w;
;         *(f32x4*)(orow + 4 * lane + 256 * j) = o; }
.Lfin_loop:
	v_mov_b32_e32 v24, 0
	v_lshl_add_u64 v[26:27], s[10:11], 0, v[10:11]
	v_lshl_add_u64 v[30:31], s[10:11], 0, v[14:15]
	s_and_saveexec_b64 s[2:3], s[0:1]
	global_load_dword v24, v[26:27], off
	s_or_b64 exec, exec, s[2:3]
	v_add_co_u32_e32 v30, vcc, s14, v30
	v_lshl_add_u64 v[32:33], v[12:13], 0, s[16:17]
	s_nop 1
	v_addc_co_u32_e32 v31, vcc, 0, v31, vcc
	global_load_dwordx2 v[72:73], v[30:31], off
	global_load_dwordx2 v[74:75], v[30:31], off offset:512
	global_load_dwordx2 v[76:77], v[30:31], off offset:1024
	global_load_dwordx2 v[78:79], v[30:31], off offset:1536
	global_load_dwordx2 v[80:81], v[30:31], off offset:2048
	global_load_dwordx2 v[82:83], v[30:31], off offset:2560
	global_load_dwordx2 v[84:85], v[30:31], off offset:3072
	global_load_dwordx2 v[86:87], v[30:31], off offset:3584
	s_waitcnt vmcnt(8)
	ds_bpermute_b32 v25, v16, v24
	s_waitcnt lgkmcnt(0)
	v_add_f32_e32 v24, v24, v25
	ds_bpermute_b32 v25, v17, v24
	s_waitcnt lgkmcnt(0)
	v_add_f32_e32 v24, v24, v25
	ds_bpermute_b32 v25, v18, v24
	s_waitcnt lgkmcnt(0)
	v_add_f32_e32 v24, v24, v25
	ds_bpermute_b32 v25, v19, v24
	s_waitcnt lgkmcnt(0)
	v_add_f32_e32 v24, v24, v25
	ds_bpermute_b32 v25, v20, v24
	s_waitcnt lgkmcnt(0)
	v_add_f32_e32 v24, v24, v25
	ds_bpermute_b32 v25, v21, v24
	s_waitcnt lgkmcnt(0)
	v_add_f32_e32 v24, v24, v25
	v_fmamk_f32 v24, v24, 0x3a000000, v22
	v_mul_f32_e32 v25, 0x4f800000, v24
	v_cmp_gt_f32_e32 vcc, s9, v24
	s_nop 1
	v_cndmask_b32_e32 v24, v24, v25, vcc
	v_sqrt_f32_e32 v25, v24
	s_nop 0
	v_add_u32_e32 v34, -1, v25
	v_add_u32_e32 v35, 1, v25
	v_fma_f32 v36, -v34, v25, v24
	v_fma_f32 v37, -v35, v25, v24
	v_cmp_ge_f32_e64 s[2:3], 0, v36
	s_nop 1
	v_cndmask_b32_e64 v25, v25, v34, s[2:3]
	v_cmp_lt_f32_e64 s[2:3], 0, v37
	s_nop 1
	v_cndmask_b32_e64 v25, v25, v35, s[2:3]
	v_mul_f32_e32 v34, 0x37800000, v25
	v_cndmask_b32_e32 v25, v25, v34, vcc
	v_cmp_class_f32_e32 vcc, v24, v23
	s_nop 1
	v_cndmask_b32_e32 v24, v25, v24, vcc
	v_div_scale_f32 v25, s[2:3], v24, v24, 1.0
	v_rcp_f32_e32 v36, v25
	s_nop 0
	v_fma_f32 v38, -v25, v36, 1.0
	s_nop 0
	s_nop 0
	v_div_scale_f32 v37, vcc, 1.0, v24, 1.0
	v_fmac_f32_e32 v36, v38, v36
	v_mul_f32_e32 v38, v37, v36
	v_fma_f32 v39, -v25, v38, v37
	v_fmac_f32_e32 v38, v39, v36
	v_fma_f32 v25, -v25, v38, v37
	v_div_fmas_f32 v25, v25, v36, v38
	v_div_fixup_f32 v36, v25, v24, 1.0
	s_waitcnt vmcnt(0)
	v_lshlrev_b32_e32 v88, 16, v72
	v_and_b32_e32 v89, 0xffff0000, v72
	v_lshlrev_b32_e32 v90, 16, v73
	v_and_b32_e32 v91, 0xffff0000, v73
	v_pk_mul_f32 v[88:89], v[36:37], v[88:89] op_sel_hi:[0,1]
	v_pk_mul_f32 v[90:91], v[36:37], v[90:91] op_sel_hi:[0,1]
	v_pk_mul_f32 v[88:89], v[40:41], v[88:89]
	v_pk_mul_f32 v[90:91], v[42:43], v[90:91]
	global_store_dwordx4 v[32:33], v[88:91], off offset:-3072
	v_lshlrev_b32_e32 v92, 16, v74
	v_and_b32_e32 v93, 0xffff0000, v74
	v_lshlrev_b32_e32 v94, 16, v75
	v_and_b32_e32 v95, 0xffff0000, v75
	v_pk_mul_f32 v[92:93], v[36:37], v[92:93] op_sel_hi:[0,1]
	v_pk_mul_f32 v[94:95], v[36:37], v[94:95] op_sel_hi:[0,1]
	v_pk_mul_f32 v[92:93], v[44:45], v[92:93]
	v_pk_mul_f32 v[94:95], v[46:47], v[94:95]
	global_store_dwordx4 v[32:33], v[92:95], off offset:-2048
	v_lshlrev_b32_e32 v96, 16, v76
	v_and_b32_e32 v97, 0xffff0000, v76
	v_lshlrev_b32_e32 v98, 16, v77
	v_and_b32_e32 v99, 0xffff0000, v77
	v_pk_mul_f32 v[96:97], v[36:37], v[96:97] op_sel_hi:[0,1]
	v_pk_mul_f32 v[98:99], v[36:37], v[98:99] op_sel_hi:[0,1]
	v_pk_mul_f32 v[96:97], v[48:49], v[96:97]
	v_pk_mul_f32 v[98:99], v[50:51], v[98:99]
	global_store_dwordx4 v[32:33], v[96:99], off offset:-1024
	v_lshlrev_b32_e32 v100, 16, v78
	v_and_b32_e32 v101, 0xffff0000, v78
	v_lshlrev_b32_e32 v102, 16, v79
	v_and_b32_e32 v103, 0xffff0000, v79
	v_pk_mul_f32 v[100:101], v[36:37], v[100:101] op_sel_hi:[0,1]
	v_pk_mul_f32 v[102:103], v[36:37], v[102:103] op_sel_hi:[0,1]
	v_pk_mul_f32 v[100:101], v[52:53], v[100:101]
	v_pk_mul_f32 v[102:103], v[54:55], v[102:103]
	global_store_dwordx4 v[12:13], v[100:103], off offset:-4096
	v_lshlrev_b32_e32 v104, 16, v80
	v_and_b32_e32 v105, 0xffff0000, v80
	v_lshlrev_b32_e32 v106, 16, v81
	v_and_b32_e32 v107, 0xffff0000, v81
	v_pk_mul_f32 v[104:105], v[36:37], v[104:105] op_sel_hi:[0,1]
	v_pk_mul_f32 v[106:107], v[36:37], v[106:107] op_sel_hi:[0,1]
	v_pk_mul_f32 v[104:105], v[56:57], v[104:105]
	v_pk_mul_f32 v[106:107], v[58:59], v[106:107]
	global_store_dwordx4 v[12:13], v[104:107], off offset:-3072
	v_lshlrev_b32_e32 v108, 16, v82
	v_and_b32_e32 v109, 0xffff0000, v82
	v_lshlrev_b32_e32 v110, 16, v83
	v_and_b32_e32 v111, 0xffff0000, v83
	v_pk_mul_f32 v[108:109], v[36:37], v[108:109] op_sel_hi:[0,1]
	v_pk_mul_f32 v[110:111], v[36:37], v[110:111] op_sel_hi:[0,1]
	v_pk_mul_f32 v[108:109], v[60:61], v[108:109]
	v_pk_mul_f32 v[110:111], v[62:63], v[110:111]
	global_store_dwordx4 v[12:13], v[108:111], off offset:-2048
	v_lshlrev_b32_e32 v112, 16, v84
	v_and_b32_e32 v113, 0xffff0000, v84
	v_lshlrev_b32_e32 v114, 16, v85
	v_and_b32_e32 v115, 0xffff0000, v85
	v_pk_mul_f32 v[112:113], v[36:37], v[112:113] op_sel_hi:[0,1]
	v_pk_mul_f32 v[114:115], v[36:37], v[114:115] op_sel_hi:[0,1]
	v_pk_mul_f32 v[112:113], v[64:65], v[112:113]
	v_pk_mul_f32 v[114:115], v[66:67], v[114:115]
	global_store_dwordx4 v[12:13], v[112:115], off offset:-1024
	v_lshlrev_b32_e32 v116, 16, v86
	v_and_b32_e32 v117, 0xffff0000, v86
	v_lshlrev_b32_e32 v118, 16, v87
	v_and_b32_e32 v119, 0xffff0000, v87
	v_pk_mul_f32 v[116:117], v[36:37], v[116:117] op_sel_hi:[0,1]
	v_pk_mul_f32 v[118:119], v[36:37], v[118:119] op_sel_hi:[0,1]
	v_pk_mul_f32 v[116:117], v[68:69], v[116:117]
	v_pk_mul_f32 v[118:119], v[70:71], v[118:119]
	global_store_dwordx4 v[12:13], v[116:119], off
	s_add_i32 s8, s8, s72
	v_lshl_add_u64 v[10:11], v[10:11], 0, s[4:5]
	v_lshl_add_u64 v[14:15], v[14:15], 0, s[12:13]
	v_lshl_add_u64 v[12:13], v[12:13], 0, s[6:7]
	s_cmpk_gt_i32 s8, 0x1fff
	s_cbranch_scc0 .Lfin_loop
